# FoX tile loop: packed f32 mul/fma/add split into single-lane ops (packed f32 issues slowly beside the partner wave's MFMAs)
# speedup vs baseline: 1.0555x; 1.0055x over previous
; #define LAS __attribute__((address_space(3)))
; __device__ __forceinline__ void item_fox(const Params& p, int l, int bl, int h, int qb, LAS unsigned char* lds) {
;     ...
;         LAS unsigned char* kb = lds + ((kt & 1) ? D_K1 : D_K0);
;         f32x16 S0, S1;
; #pragma unroll
;         for (int r = 0; r < 16; ++r) { S0[r] = 0.f; S1[r] = 0.f; }
; #pragma unroll
;         for (int ks = 0; ks < 8; ++ks) {
;             const bf16x8 a0 = *(const LAS bf16x8*)(kb + rowA * 272 + ks * 32 + hi * 16);
;             const bf16x8 a1 = *(const LAS bf16x8*)(kb + (rowA + 32) * 272 + ks * 32 + hi * 16);
;             S0 = __builtin_amdgcn_mfma_f32_32x32x16_bf16(a0, Qf[ks], S0, 0, 0, 0);
;             S1 = __builtin_amdgcn_mfma_f32_32x32x16_bf16(a1, Qf[ks], S1, 0, 0, 0);
;         }
;         const int kb0 = k0 + 8 * hi;
; #pragma unroll
;         for (int q4 = 0; q4 < 4; ++q4) {
;             const f32x4 c0 = *(const LAS f32x4*)(cumL + kb0 + (q4 & 1) * 4 + (q4 >> 1) * 16);
;             const f32x4 c1 = *(const LAS f32x4*)(cumL + kb0 + 32 + (q4 & 1) * 4 + (q4 >> 1) * 16);
; #pragma unroll
;             for (int j = 0; j < 4; ++j) { const int r = q4 * 4 + j; S0[r] = fmaf(S0[r], C2, c0[j]); S1[r] = fmaf(S1[r], C2, c1[j]); }
;         }
;         if (k0 + 63 > qw_lo) {
;             const int dq = qrow - kb0;
; #pragma unroll
;             for (int r = 0; r < 16; ++r) { const int ko = (r & 7) + 16 * (r >> 3); if (ko > dq) S0[r] = -__builtin_inff(); if (ko + 32 > dq) S1[r] = -__builtin_inff(); }
.LBB0_1005:
	s_bfe_i32 s0, s24, 0x10000
	s_and_b32 s0, s0, 0x4400
	v_add_u32_e32 v0, s0, v193
	ds_read_b128 v[2:5], v0 offset:8704
	ds_read_b128 v[6:9], v0
	ds_read_b128 v[10:13], v0 offset:32
	ds_read_b128 v[212:215], v0 offset:8736
	ds_read_b128 v[216:219], v0 offset:64
	ds_read_b128 v[220:223], v0 offset:8768
	ds_read_b128 v[224:227], v0 offset:96
	ds_read_b128 v[228:231], v0 offset:8800
	ds_read_b128 v[232:235], v0 offset:128
	s_add_i32 s0, s30, -1
	s_cmp_le_i32 s0, s26
	s_waitcnt lgkmcnt(8)
	v_mfma_f32_32x32x16_bf16 v[80:95], v[2:5], v[112:115], 0
	ds_read_b128 v[2:5], v0 offset:8832
	s_waitcnt lgkmcnt(8)
	v_mfma_f32_32x32x16_bf16 v[96:111], v[6:9], v[112:115], 0
	ds_read_b128 v[6:9], v0 offset:160
	s_waitcnt lgkmcnt(8)
	v_mfma_f32_32x32x16_bf16 v[96:111], v[10:13], v[116:119], v[96:111]
	ds_read_b128 v[10:13], v0 offset:8864
	s_waitcnt lgkmcnt(8)
	v_mfma_f32_32x32x16_bf16 v[80:95], v[212:215], v[116:119], v[80:95]
	ds_read_b128 v[212:215], v0 offset:192
	s_waitcnt lgkmcnt(8)
	v_mfma_f32_32x32x16_bf16 v[96:111], v[216:219], v[120:123], v[96:111]
	ds_read_b128 v[216:219], v0 offset:8896
	s_waitcnt lgkmcnt(8)
	v_mfma_f32_32x32x16_bf16 v[80:95], v[220:223], v[120:123], v[80:95]
	ds_read_b128 v[220:223], v0 offset:224
	s_waitcnt lgkmcnt(8)
	v_mfma_f32_32x32x16_bf16 v[96:111], v[224:227], v[124:127], v[96:111]
	ds_read_b128 v[224:227], v0 offset:8928
	s_waitcnt lgkmcnt(8)
	v_mfma_f32_32x32x16_bf16 v[80:95], v[228:231], v[124:127], v[80:95]
	s_waitcnt lgkmcnt(7)
	v_mfma_f32_32x32x16_bf16 v[96:111], v[232:235], v[128:131], v[96:111]
	s_waitcnt lgkmcnt(6)
	v_mfma_f32_32x32x16_bf16 v[80:95], v[2:5], v[128:131], v[80:95]
	s_waitcnt lgkmcnt(5)
	v_mfma_f32_32x32x16_bf16 v[96:111], v[6:9], v[132:135], v[96:111]
	s_waitcnt lgkmcnt(4)
	v_mfma_f32_32x32x16_bf16 v[80:95], v[10:13], v[132:135], v[80:95]
	s_waitcnt lgkmcnt(3)
	v_mfma_f32_32x32x16_bf16 v[96:111], v[212:215], v[136:139], v[96:111]
	s_waitcnt lgkmcnt(2)
	v_mfma_f32_32x32x16_bf16 v[80:95], v[216:219], v[136:139], v[80:95]
	s_waitcnt lgkmcnt(1)
	v_mfma_f32_32x32x16_bf16 v[96:111], v[220:223], v[140:143], v[96:111]
	s_waitcnt lgkmcnt(0)
	v_mfma_f32_32x32x16_bf16 v[80:95], v[224:227], v[140:143], v[80:95]
	ds_read_b128 v[212:215], v195 offset:128
	ds_read_b128 v[216:219], v195
	ds_read_b128 v[220:223], v195 offset:16
	ds_read_b128 v[224:227], v195 offset:144
	ds_read_b128 v[6:9], v195 offset:64
	ds_read_b128 v[228:231], v195 offset:192
	ds_read_b128 v[10:13], v195 offset:80
	ds_read_b128 v[232:235], v195 offset:208
	s_waitcnt lgkmcnt(5)
	s_nop 0
	v_fma_f32 v102, v102, s36, v222
	v_fma_f32 v103, v103, s36, v223
	s_waitcnt lgkmcnt(3)
	v_fma_f32 v8, v106, s36, v8
	v_fma_f32 v9, v107, s36, v9
	v_fma_f32 v100, v100, s36, v220
	v_fma_f32 v101, v101, s36, v221
	s_waitcnt lgkmcnt(1)
	v_fma_f32 v2, v110, s36, v12
	v_fma_f32 v3, v111, s36, v13
	v_fma_f32 v4, v108, s36, v10
	v_fma_f32 v5, v109, s36, v11
	v_fma_f32 v12, v104, s36, v6
	v_fma_f32 v13, v105, s36, v7
	v_fma_f32 v98, v98, s36, v218
	v_fma_f32 v99, v99, s36, v219
	v_fma_f32 v96, v96, s36, v216
	v_fma_f32 v97, v97, s36, v217
	s_waitcnt lgkmcnt(0)
	v_fma_f32 v6, v94, s36, v234
	v_fma_f32 v7, v95, s36, v235
	v_fma_f32 v10, v92, s36, v232
	v_fma_f32 v11, v93, s36, v233
	v_fma_f32 v14, v90, s36, v230
	v_fma_f32 v15, v91, s36, v231
	v_fma_f32 v88, v88, s36, v228
	v_fma_f32 v89, v89, s36, v229
	v_fma_f32 v86, v86, s36, v226
	v_fma_f32 v87, v87, s36, v227
	v_fma_f32 v84, v84, s36, v224
	v_fma_f32 v85, v85, s36, v225
	v_fma_f32 v82, v82, s36, v214
	v_fma_f32 v83, v83, s36, v215
	v_fma_f32 v80, v80, s36, v212
	v_fma_f32 v81, v81, s36, v213
	s_cbranch_scc1 .LBB0_1007
	v_cmp_gt_i32_e64 s[96:97], 22, v194
	v_cmp_gt_i32_e32 vcc, 23, v194
	v_cmp_gt_i32_e64 s[94:95], 21, v194
	v_cmp_gt_i32_e64 s[92:93], 20, v194
	v_cndmask_b32_e32 v3, v3, v208, vcc
	s_and_b64 vcc, vcc, s[96:97]
	v_cndmask_b32_e32 v2, v2, v208, vcc
	s_and_b64 vcc, vcc, s[94:95]
	v_cmp_gt_i32_e64 s[90:91], 19, v194
	v_cndmask_b32_e32 v5, v5, v208, vcc
	s_and_b64 vcc, vcc, s[92:93]
	v_cmp_gt_i32_e64 s[88:89], 18, v194
	v_cndmask_b32_e32 v4, v4, v208, vcc
	s_and_b64 vcc, vcc, s[90:91]
	v_cmp_gt_i32_e64 s[86:87], 17, v194
	v_cndmask_b32_e32 v9, v9, v208, vcc
	s_and_b64 vcc, vcc, s[88:89]
	v_cmp_gt_i32_e64 s[84:85], 16, v194
	v_cndmask_b32_e32 v8, v8, v208, vcc
	s_and_b64 vcc, vcc, s[86:87]
	v_cmp_gt_i32_e64 s[82:83], 7, v194
	v_cndmask_b32_e32 v13, v13, v208, vcc
	s_and_b64 vcc, vcc, s[84:85]
	v_cmp_gt_i32_e64 s[80:81], 6, v194
	v_cndmask_b32_e32 v12, v12, v208, vcc
	s_and_b64 vcc, vcc, s[82:83]
	v_cmp_gt_i32_e64 s[78:79], 5, v194
	v_cndmask_b32_e32 v103, v103, v208, vcc
	s_and_b64 vcc, vcc, s[80:81]
	v_cmp_gt_i32_e64 s[76:77], 4, v194
	v_cndmask_b32_e32 v102, v102, v208, vcc
	s_and_b64 vcc, vcc, s[78:79]
	v_cmp_gt_i32_e64 s[74:75], 3, v194
	v_cndmask_b32_e32 v101, v101, v208, vcc
	s_and_b64 vcc, vcc, s[76:77]
	v_cmp_gt_i32_e64 s[72:73], 2, v194
	v_cndmask_b32_e32 v100, v100, v208, vcc
	s_and_b64 vcc, vcc, s[74:75]
	v_cmp_gt_i32_e64 s[70:71], 1, v194
	v_cndmask_b32_e32 v99, v99, v208, vcc
	s_and_b64 vcc, vcc, s[72:73]
	v_cmp_gt_i32_e64 s[68:69], 0, v194
	v_cndmask_b32_e32 v98, v98, v208, vcc
	s_and_b64 vcc, vcc, s[70:71]
	v_cndmask_b32_e32 v97, v97, v208, vcc
	s_and_b64 vcc, vcc, s[68:69]
	v_cmp_gt_i32_e64 s[64:65], 54, v194
	v_cndmask_b32_e32 v96, v96, v208, vcc
	v_cmp_gt_i32_e32 vcc, 55, v194
	v_cmp_gt_i32_e64 s[62:63], 53, v194
	v_cmp_gt_i32_e64 s[60:61], 52, v194
	v_cndmask_b32_e32 v7, v7, v208, vcc
	s_and_b64 vcc, vcc, s[64:65]
	v_cndmask_b32_e32 v6, v6, v208, vcc
	s_and_b64 vcc, vcc, s[62:63]
	v_cmp_gt_i32_e64 s[58:59], 51, v194
	v_cndmask_b32_e32 v11, v11, v208, vcc
	s_and_b64 vcc, vcc, s[60:61]
; __device__ __forceinline__ void item_fox(const Params& p, int l, int bl, int h, int qb, LAS unsigned char* lds) {
;     ...
;         if (k0 + 63 > qw_lo) {
;             const int dq = qrow - kb0;
; #pragma unroll
;             for (int r = 0; r < 16; ++r) { const int ko = (r & 7) + 16 * (r >> 3); if (ko > dq) S0[r] = -__builtin_inff(); if (ko + 32 > dq) S1[r] = -__builtin_inff(); }
	v_cmp_gt_i32_e64 s[56:57], 50, v194
	v_cndmask_b32_e32 v10, v10, v208, vcc
	s_and_b64 vcc, vcc, s[58:59]
	v_cmp_gt_i32_e64 s[54:55], 49, v194
	v_cndmask_b32_e32 v15, v15, v208, vcc
	s_and_b64 vcc, vcc, s[56:57]
	v_cmp_gt_i32_e64 s[52:53], 48, v194
	v_cndmask_b32_e32 v14, v14, v208, vcc
	s_and_b64 vcc, vcc, s[54:55]
	v_cmp_gt_i32_e64 s[50:51], 39, v194
	v_cndmask_b32_e32 v89, v89, v208, vcc
	s_and_b64 vcc, vcc, s[52:53]
	v_cmp_gt_i32_e64 s[48:49], 38, v194
	v_cndmask_b32_e32 v88, v88, v208, vcc
	s_and_b64 vcc, vcc, s[50:51]
	v_cmp_gt_i32_e64 s[46:47], 37, v194
	v_cndmask_b32_e32 v87, v87, v208, vcc
	s_and_b64 vcc, vcc, s[48:49]
	v_cmp_gt_i32_e64 s[42:43], 36, v194
	v_cndmask_b32_e32 v86, v86, v208, vcc
	s_and_b64 vcc, vcc, s[46:47]
	v_cmp_gt_i32_e64 s[40:41], 35, v194
	v_cndmask_b32_e32 v85, v85, v208, vcc
	s_and_b64 vcc, vcc, s[42:43]
	v_cmp_gt_i32_e64 s[38:39], 34, v194
	v_cndmask_b32_e32 v84, v84, v208, vcc
	s_and_b64 vcc, vcc, s[40:41]
	v_cmp_gt_i32_e64 s[0:1], 33, v194
	v_cndmask_b32_e32 v83, v83, v208, vcc
	s_and_b64 vcc, vcc, s[38:39]
	v_cmp_gt_i32_e64 s[66:67], 32, v194
	v_cndmask_b32_e32 v82, v82, v208, vcc
	s_and_b64 vcc, vcc, s[0:1]
	v_readlane_b32 s88, v253, 47
	v_cndmask_b32_e32 v81, v81, v208, vcc
	s_and_b64 vcc, vcc, s[66:67]
	s_mov_b64 s[90:91], 0x800
	v_readlane_b32 s89, v253, 48
	s_movk_i32 s87, 0x204
	s_mov_b32 s86, 0xd000
	s_mov_b32 s85, 0x800000
	s_movk_i32 s84, 0x2000
	v_readlane_b32 s82, v253, 45
	v_cndmask_b32_e32 v80, v80, v208, vcc
	v_readlane_b32 s83, v253, 46
; __device__ __forceinline__ unsigned cvtpk(float lo, float hi) { unsigned r; asm volatile("v_cvt_pk_bf16_f32 %0, %1, %2" : "=v"(r) : "v"(lo), "v"(hi)); return r; }
; __device__ __forceinline__ void item_fox(const Params& p, int l, int bl, int h, int qb, LAS unsigned char* lds) {
;     ...
;         float mx = S0[0];
; #pragma unroll
;         for (int r = 1; r < 16; ++r) mx = fmaxf(mx, S0[r]);
; #pragma unroll
;         for (int r = 0; r < 16; ++r) mx = fmaxf(mx, S1[r]);
;         mx = fmaxf(mx, __shfl_xor(mx, 32));
;         const float mnew = fmaxf(mrun, mx), alpha = __builtin_amdgcn_exp2f(mrun - mnew); mrun = mnew;
;         float ps = 0.f;
; #pragma unroll
;         for (int r = 0; r < 16; ++r) { S0[r] = __builtin_amdgcn_exp2f(S0[r] - mnew); S1[r] = __builtin_amdgcn_exp2f(S1[r] - mnew); ps += S0[r] + S1[r]; }
;         lrun = lrun * alpha + ps;
; #pragma unroll
;         for (int i = 0; i < 4; ++i) O[i] *= alpha;
; #pragma unroll
;         for (int j = 0; j < 2; ++j)
; #pragma unroll
;             for (int e = 0; e < 4; ++e) { Pk[j][e] = cvtpk(S0[8 * j + 2 * e], S0[8 * j + 2 * e + 1]); Pk[2 + j][e] = cvtpk(S1[8 * j + 2 * e], S1[8 * j + 2 * e + 1]); }
.LBB0_1007:
	v_max_f32_e32 v0, v97, v97
	v_max_f32_e32 v90, v96, v96
	v_max_f32_e32 v0, v90, v0
	v_max3_f32 v0, v0, v98, v99
	v_max3_f32 v0, v0, v100, v101
	v_max3_f32 v0, v0, v102, v103
	v_max3_f32 v0, v0, v12, v13
	v_max3_f32 v0, v0, v8, v9
	v_max3_f32 v0, v0, v4, v5
	v_max3_f32 v0, v0, v2, v3
	v_max3_f32 v0, v0, v80, v81
	v_max3_f32 v0, v0, v82, v83
	v_max3_f32 v0, v0, v84, v85
	v_max3_f32 v0, v0, v86, v87
	v_max3_f32 v0, v0, v88, v89
	v_max3_f32 v0, v0, v14, v15
	v_max3_f32 v0, v0, v10, v11
	v_max3_f32 v0, v0, v6, v7
	v_mov_b32_e32 v90, v0
	s_nop 1
	v_permlane32_swap_b32_e32 v0, v90
	v_max3_f32 v106, v196, v0, v90
	v_sub_f32_e32 v90, v96, v106
	v_sub_f32_e32 v80, v80, v106
	v_exp_f32_e32 v92, v90
	v_exp_f32_e32 v93, v80
	v_sub_f32_e32 v80, v97, v106
	v_sub_f32_e32 v81, v81, v106
	v_exp_f32_e32 v94, v80
	v_exp_f32_e32 v95, v81
	v_sub_f32_e32 v81, v98, v106
	v_add_f32_e32 v80, v92, v93
	v_exp_f32_e32 v107, v81
	v_sub_f32_e32 v81, v82, v106
	v_exp_f32_e32 v108, v81
	v_add_f32_e32 v80, 0, v80
	v_add_f32_e32 v81, v94, v95
	v_add_f32_e32 v90, v81, v80
	v_sub_f32_e32 v80, v99, v106
	v_exp_f32_e32 v109, v80
	v_sub_f32_e32 v80, v83, v106
	v_exp_f32_e32 v110, v80
	v_sub_f32_e32 v80, v100, v106
	v_exp_f32_e32 v81, v80
	v_sub_f32_e32 v80, v84, v106
	v_exp_f32_e32 v83, v80
	v_sub_f32_e32 v80, v101, v106
	v_sub_f32_e32 v82, v85, v106
	v_exp_f32_e32 v80, v80
	v_exp_f32_e32 v82, v82
	v_add_f32_e32 v91, v107, v108
	v_add_f32_e32 v84, v91, v90
	v_add_f32_e32 v85, v109, v110
	v_add_f32_e32 v90, v85, v84
	v_add_f32_e32 v84, v80, v82
	v_add_f32_e32 v85, v81, v83
	v_sub_f32_e32 v12, v12, v106
	v_add_f32_e32 v85, v85, v90
	v_add_f32_e32 v84, v84, v85
	v_sub_f32_e32 v85, v102, v106
	v_exp_f32_e32 v97, v85
	v_sub_f32_e32 v85, v86, v106
	v_exp_f32_e32 v91, v85
	v_sub_f32_e32 v85, v103, v106
	v_exp_f32_e32 v96, v85
	v_sub_f32_e32 v85, v87, v106
	v_exp_f32_e32 v99, v12
	v_sub_f32_e32 v12, v88, v106
	v_exp_f32_e32 v90, v85
	v_exp_f32_e32 v101, v12
	v_sub_f32_e32 v12, v13, v106
	v_exp_f32_e32 v98, v12
	v_sub_f32_e32 v12, v89, v106
	v_exp_f32_e32 v100, v12
	v_add_f32_e32 v12, v96, v90
	v_add_f32_e32 v13, v97, v91
	v_sub_f32_e32 v8, v8, v106
	v_add_f32_e32 v13, v13, v84
	v_add_f32_e32 v84, v12, v13
	v_add_f32_e32 v12, v98, v100
	v_add_f32_e32 v13, v99, v101
	v_sub_f32_e32 v4, v4, v106
	v_add_f32_e32 v13, v13, v84
	v_add_f32_e32 v84, v12, v13
	v_exp_f32_e32 v13, v8
	v_sub_f32_e32 v8, v14, v106
	v_exp_f32_e32 v103, v8
	v_sub_f32_e32 v8, v9, v106
	v_exp_f32_e32 v12, v8
	v_sub_f32_e32 v8, v15, v106
	v_exp_f32_e32 v9, v4
	v_sub_f32_e32 v4, v10, v106
	v_exp_f32_e32 v102, v8
	v_exp_f32_e32 v15, v4
	v_sub_f32_e32 v4, v5, v106
	v_sub_f32_e32 v2, v2, v106
	v_exp_f32_e32 v8, v4
	v_sub_f32_e32 v4, v11, v106
	v_exp_f32_e32 v11, v2
	v_sub_f32_e32 v2, v6, v106
	v_exp_f32_e32 v14, v4
	v_exp_f32_e32 v105, v2
	v_sub_f32_e32 v2, v3, v106
	v_exp_f32_e32 v10, v2
	v_sub_f32_e32 v2, v7, v106
	v_add_f32_e32 v4, v12, v102
	v_add_f32_e32 v5, v13, v103
	v_exp_f32_e32 v104, v2
	v_add_f32_e32 v5, v5, v84
	v_sub_f32_e32 v0, v196, v106
	v_add_f32_e32 v84, v4, v5
	v_add_f32_e32 v4, v8, v14
	v_add_f32_e32 v5, v9, v15
	v_exp_f32_e32 v0, v0
	v_add_f32_e32 v2, v5, v84
	v_add_f32_e32 v4, v4, v2
	v_add_f32_e32 v2, v10, v104
	v_add_f32_e32 v3, v11, v105
	v_mul_f32_e32 v78, v78, v0
	v_mul_f32_e32 v79, v79, v0
	v_add_f32_e32 v3, v3, v4
	v_add_f32_e32 v2, v2, v3
	v_fmac_f32_e32 v2, v187, v0
	v_mul_f32_e32 v76, v76, v0
	v_mul_f32_e32 v77, v77, v0
	v_mul_f32_e32 v74, v74, v0
	v_mul_f32_e32 v75, v75, v0
	v_mul_f32_e32 v72, v72, v0
	v_mul_f32_e32 v73, v73, v0
	v_mul_f32_e32 v70, v70, v0
	v_mul_f32_e32 v71, v71, v0
	v_mul_f32_e32 v68, v68, v0
	v_mul_f32_e32 v69, v69, v0
	v_mul_f32_e32 v66, v66, v0
	v_mul_f32_e32 v67, v67, v0
	v_mul_f32_e32 v64, v64, v0
	v_mul_f32_e32 v65, v65, v0
	v_mul_f32_e32 v62, v62, v0
	v_mul_f32_e32 v63, v63, v0
	v_mul_f32_e32 v60, v60, v0
	v_mul_f32_e32 v61, v61, v0
	v_mul_f32_e32 v58, v58, v0
	v_mul_f32_e32 v59, v59, v0
	v_mul_f32_e32 v56, v56, v0
	v_mul_f32_e32 v57, v57, v0
	v_mul_f32_e32 v54, v54, v0
	v_mul_f32_e32 v55, v55, v0
	v_mul_f32_e32 v52, v52, v0
	v_mul_f32_e32 v53, v53, v0
	v_mul_f32_e32 v50, v50, v0
	v_mul_f32_e32 v51, v51, v0
	v_mul_f32_e32 v48, v48, v0
	v_mul_f32_e32 v49, v49, v0
	v_mul_f32_e32 v46, v46, v0
	v_mul_f32_e32 v47, v47, v0
	v_mul_f32_e32 v44, v44, v0
	v_mul_f32_e32 v45, v45, v0
	v_mul_f32_e32 v42, v42, v0
	v_mul_f32_e32 v43, v43, v0
	v_mul_f32_e32 v40, v40, v0
	v_mul_f32_e32 v41, v41, v0
	v_mul_f32_e32 v38, v38, v0
	v_mul_f32_e32 v39, v39, v0
	v_mul_f32_e32 v36, v36, v0
	v_mul_f32_e32 v37, v37, v0
	v_mul_f32_e32 v34, v34, v0
	v_mul_f32_e32 v35, v35, v0
	v_mul_f32_e32 v32, v32, v0
	v_mul_f32_e32 v33, v33, v0
	v_mul_f32_e32 v30, v30, v0
	v_mul_f32_e32 v31, v31, v0
	v_mul_f32_e32 v28, v28, v0
	v_mul_f32_e32 v29, v29, v0
	v_mul_f32_e32 v26, v26, v0
	v_mul_f32_e32 v27, v27, v0
	v_mul_f32_e32 v24, v24, v0
	v_mul_f32_e32 v25, v25, v0
	v_mul_f32_e32 v22, v22, v0
	v_mul_f32_e32 v23, v23, v0
	v_mul_f32_e32 v20, v20, v0
	v_mul_f32_e32 v21, v21, v0
	v_mul_f32_e32 v18, v18, v0
	v_mul_f32_e32 v19, v19, v0
	v_mul_f32_e32 v16, v16, v0
	v_mul_f32_e32 v17, v17, v0
	v_mov_b32_e32 v187, v2
	v_mov_b32_e32 v196, v106
	v_cvt_pk_bf16_f32 v92, v92, v94
	v_cvt_pk_bf16_f32 v84, v93, v95
	v_cvt_pk_bf16_f32 v93, v107, v109
	v_cvt_pk_bf16_f32 v85, v108, v110
	v_cvt_pk_bf16_f32 v94, v81, v80
	v_cvt_pk_bf16_f32 v86, v83, v82
	v_cvt_pk_bf16_f32 v95, v97, v96
	v_cvt_pk_bf16_f32 v87, v91, v90
	v_cvt_pk_bf16_f32 v88, v99, v98
	v_cvt_pk_bf16_f32 v80, v101, v100
	v_cvt_pk_bf16_f32 v89, v13, v12
	v_cvt_pk_bf16_f32 v81, v103, v102
	v_cvt_pk_bf16_f32 v90, v9, v8
	v_cvt_pk_bf16_f32 v82, v15, v14
	v_cvt_pk_bf16_f32 v91, v11, v10
	v_cvt_pk_bf16_f32 v83, v105, v104
	s_and_b64 s[0:1], s[28:29], s[44:45]
	s_andn2_b64 vcc, exec, s[0:1]
	s_cbranch_vccnz .LBB0_1001
